# FoX decay-bound tile search vectorised (2 loads + ballot instead of serial dependent loads)
# baseline (speedup 1.0000x reference)
.LBB0_456:
	s_ashr_i32 s15, s2, 6
	s_sub_i32 s11, 63, s15
	s_lshl_b32 s6, s11, 7
	s_and_b32 s3, s2, 63
	v_add_u32_e32 v116, s6, v135
	s_lshl_b32 s12, s3, 13
	v_ashrrev_i32_e32 v117, 31, v116
	v_lshl_add_u64 v[2:3], s[12:13], 0, v[116:117]
	v_lshlrev_b64 v[2:3], 7, v[2:3]
	s_lshl_b32 s7, s3, 15
	v_lshl_add_u64 v[2:3], v[110:111], 0, v[2:3]
	s_add_u32 s16, s60, s7
	s_mov_b32 s7, s13
	global_load_dwordx4 v[66:69], v[2:3], off
	global_load_dwordx4 v[70:73], v[2:3], off offset:32
	global_load_dwordx4 v[74:77], v[2:3], off offset:64
	global_load_dwordx4 v[78:81], v[2:3], off offset:96
	s_addc_u32 s17, s61, 0
	s_lshl_b64 s[18:19], s[6:7], 2
	v_lshl_add_u64 v[2:3], v[116:117], 2, s[16:17]
	s_add_u32 s18, s16, s18
	s_addc_u32 s19, s17, s19
	global_load_dword v34, v[2:3], off
	s_nop 0
	global_load_dword v2, v103, s[18:19]
	s_lshl_b32 s20, s11, 1
	s_or_b32 s22, s20, 1
	s_lshl_b32 s7, s15, 7
	s_sub_i32 s12, 0x1fbf, s7
	s_mov_b32 s11, s22
	v_mbcnt_lo_u32_b32 v3, -1, 0
	v_mbcnt_hi_u32_b32 v3, -1, v3
	s_add_i32 s23, s22, -1
	v_sub_u32_e32 v4, s23, v3
	v_subrev_u32_e32 v6, 64, v4
	v_cmp_le_i32_e64 s[80:81], 0, v4
	v_cmp_le_i32_e64 s[82:83], 0, v6
	v_max_i32_e32 v5, 0, v4
	v_max_i32_e32 v7, 0, v6
	v_lshlrev_b32_e32 v5, 8, v5
	v_lshlrev_b32_e32 v7, 8, v7
	global_load_dword v5, v5, s[16:17] offset:252
	global_load_dword v7, v7, s[16:17] offset:252
	s_waitcnt vmcnt(0)
	v_sub_f32_e32 v5, v2, v5
	v_sub_f32_e32 v7, v2, v7
	v_cmp_lt_f32_e64 s[76:77], v5, -v134
	v_cmp_lt_f32_e64 s[78:79], v7, -v134
	s_and_b64 s[76:77], s[76:77], s[80:81]
	s_and_b64 s[78:79], s[78:79], s[82:83]
	s_mov_b32 s21, 0
	s_cmp_lg_u64 s[78:79], 0
	s_cbranch_scc0 .Ljm_a
	s_ff1_i32_b64 s21, s[78:79]
	s_sub_i32 s21, s22, s21
	s_sub_i32 s21, s21, 64
.Ljm_a:
	s_cmp_lg_u64 s[76:77], 0
	s_cbranch_scc0 .Ljm_b
	s_ff1_i32_b64 s21, s[76:77]
	s_sub_i32 s21, s22, s21
.Ljm_b:
.LBB0_460:
	s_sub_i32 s11, s22, s21
	v_mov_b32_e32 v33, 0
	s_cmp_lt_i32 s11, 0
	v_mov_b32_e32 v32, v33
	v_mov_b32_e32 v31, v33
	v_mov_b32_e32 v30, v33
	v_mov_b32_e32 v29, v33
	v_mov_b32_e32 v28, v33
	v_mov_b32_e32 v27, v33
	v_mov_b32_e32 v26, v33
	v_mov_b32_e32 v25, v33
	v_mov_b32_e32 v24, v33
	v_mov_b32_e32 v23, v33
	v_mov_b32_e32 v22, v33
	v_mov_b32_e32 v21, v33
	v_mov_b32_e32 v20, v33
	v_mov_b32_e32 v19, v33
	v_mov_b32_e32 v18, v33
	v_mov_b32_e32 v17, v33
	v_mov_b32_e32 v16, v33
	v_mov_b32_e32 v15, v33
	v_mov_b32_e32 v14, v33
	v_mov_b32_e32 v13, v33
	v_mov_b32_e32 v12, v33
	v_mov_b32_e32 v11, v33
	v_mov_b32_e32 v10, v33
	v_mov_b32_e32 v9, v33
	v_mov_b32_e32 v8, v33
	v_mov_b32_e32 v7, v33
	v_mov_b32_e32 v6, v33
	v_mov_b32_e32 v5, v33
	v_mov_b32_e32 v4, v33
	v_mov_b32_e32 v3, v33
	v_mov_b32_e32 v2, v33
	v_mov_b32_e32 v115, v33
	s_cbranch_scc1 .LBB0_455
	s_lshl_b32 s12, s3, 20
	s_add_u32 s62, s56, s12
	s_addc_u32 s63, s57, 0
	s_add_u32 s64, s58, s12
	s_mov_b32 s23, s13
	s_addc_u32 s65, s59, 0
	s_lshl_b64 s[24:25], s[22:23], 13
	s_add_u32 s28, s62, s24
	s_addc_u32 s29, s63, s25
	s_add_u32 s24, s64, s24
	s_addc_u32 s25, s65, s25
	v_lshl_add_u64 v[2:3], s[28:29], 0, v[102:103]
	v_lshl_add_u64 v[4:5], v[2:3], 0, v[104:105]
	v_lshl_add_u64 v[6:7], s[24:25], 0, v[102:103]
	v_lshl_add_u64 v[2:3], v[2:3], 0, v[106:107]
	v_lshl_add_u64 v[8:9], v[6:7], 0, v[104:105]
	global_load_dwordx4 v[86:89], v[4:5], off
	global_load_dwordx4 v[90:93], v[8:9], off
	v_lshl_add_u64 v[4:5], v[6:7], 0, v[106:107]
	global_load_dwordx4 v[94:97], v[2:3], off
	global_load_dwordx4 v[98:101], v[4:5], off
	v_mov_b32_e32 v82, v103
	v_mov_b32_e32 v83, v103
	v_mov_b32_e32 v84, v103
	v_mov_b32_e32 v85, v103
	s_and_saveexec_b64 s[66:67], s[4:5]
	s_cbranch_execz .LBB0_463
	s_lshl_b32 s12, s22, 6
	s_lshl_b64 s[24:25], s[12:13], 2
	s_add_u32 s24, s16, s24
	s_addc_u32 s25, s17, s25
	global_load_dwordx4 v[82:85], v114, s[24:25]
